# attention tile loop: exp2 of (score - max) without the below-2^-126 range-scaling wrapper (compare, +64, ldexp -64) around each v_exp_f32; per-XCD queues kept
# speedup vs baseline: 1.0102x; 1.0011x over previous
.LBB0_810:
	s_nop 8
	v_max_f32_e32 v64, v48, v48
	v_max_f32_e32 v65, v32, v32
	v_max_f32_e32 v64, v65, v64
	v_max3_f32 v64, v64, v33, v49
	v_max3_f32 v64, v64, v34, v50
	v_max3_f32 v64, v64, v35, v51
	v_max3_f32 v64, v64, v36, v52
	v_max3_f32 v64, v64, v37, v53
	v_max3_f32 v64, v64, v38, v54
	v_max3_f32 v64, v64, v39, v55
	v_max3_f32 v64, v64, v40, v56
	v_max3_f32 v64, v64, v41, v57
	v_max3_f32 v64, v64, v42, v58
	v_max3_f32 v64, v64, v43, v59
	v_max3_f32 v64, v64, v44, v60
	v_max3_f32 v64, v64, v45, v61
	v_max3_f32 v64, v64, v46, v62
	v_max3_f32 v64, v64, v47, v63
	ds_bpermute_b32 v65, v191, v64
	s_waitcnt vmcnt(7)
	v_lshrrev_b32_e32 v72, 16, v168
	s_waitcnt vmcnt(3)
	v_and_or_b32 v72, v172, s31, v72
	v_add_u32_e32 v93, v203, v204
	s_add_i32 s43, s43, 64
	s_waitcnt lgkmcnt(0)
	v_max3_f32 v195, v234, v64, v65
	v_sub_f32_e32 v32, v32, v195
	v_sub_f32_e32 v48, v48, v195
	v_exp_f32_e32 v32, v32
	v_sub_f32_e32 v33, v33, v195
	v_mov_b32_e32 v68, v32
	v_mov_b32_e32 v32, v48
	v_exp_f32_e32 v32, v32
	v_exp_f32_e32 v33, v33
	v_mov_b32_e32 v70, v32
	v_mov_b32_e32 v76, v33
	v_sub_f32_e32 v32, v49, v195
	v_sub_f32_e32 v34, v34, v195
	v_sub_f32_e32 v41, v41, v195
	v_exp_f32_e32 v32, v32
	v_sub_f32_e32 v42, v42, v195
	v_exp_f32_e32 v34, v34
	v_mov_b32_e32 v88, v32
	v_sub_f32_e32 v43, v43, v195
	v_mov_b32_e32 v77, v34
	v_sub_f32_e32 v32, v50, v195
	v_sub_f32_e32 v34, v35, v195
	v_sub_f32_e32 v44, v44, v195
	v_exp_f32_e32 v32, v32
	v_sub_f32_e32 v45, v45, v195
	v_exp_f32_e32 v34, v34
	v_mov_b32_e32 v89, v32
	v_sub_f32_e32 v46, v46, v195
	v_mov_b32_e32 v78, v34
	v_sub_f32_e32 v32, v51, v195
	v_sub_f32_e32 v34, v36, v195
	v_sub_f32_e32 v71, v234, v195
	v_exp_f32_e32 v32, v32
	v_add_f32_e32 v69, v76, v88
	v_exp_f32_e32 v34, v34
	v_mov_b32_e32 v91, v32
	v_add_f32_e32 v90, v77, v89
	v_mov_b32_e32 v49, v34
	v_sub_f32_e32 v32, v52, v195
	v_add_f32_e32 v92, v78, v91
	v_cvt_pk_bf16_f32 v76, v68, v76
	v_cvt_pk_bf16_f32 v77, v77, v78
	s_add_i32 s40, s40, 1
	v_sub_f32_e32 v33, v37, v195
	v_exp_f32_e32 v32, v32
	v_subrev_u32_e32 v232, 64, v232
	v_exp_f32_e32 v33, v33
	v_mov_b32_e32 v35, v32
	v_mov_b32_e32 v48, v33
	v_sub_f32_e32 v32, v53, v195
	v_sub_f32_e32 v34, v38, v195
	v_cvt_pk_bf16_f32 v78, v49, v48
	v_lshl_add_u64 v[198:199], v[198:199], 0, s[18:19]
	v_exp_f32_e32 v32, v32
	s_cmp_eq_u32 s14, s43
	v_exp_f32_e32 v36, v34
	v_mov_b32_e32 v34, v32
	v_pk_add_f32 v[32:33], v[48:49], v[34:35]
	v_mov_b32_e32 v53, v36
	v_sub_f32_e32 v36, v54, v195
	v_lshl_add_u64 v[200:201], v[200:201], 0, s[18:19]
	s_nop 0
	v_sub_f32_e32 v37, v39, v195
	v_exp_f32_e32 v36, v36
	s_nop 0
	v_exp_f32_e32 v37, v37
	v_mov_b32_e32 v39, v36
	v_mov_b32_e32 v52, v37
	v_sub_f32_e32 v36, v55, v195
	v_sub_f32_e32 v38, v40, v195
	v_cvt_pk_bf16_f32 v79, v53, v52
	v_exp_f32_e32 v36, v36
	s_nop 0
	v_exp_f32_e32 v40, v38
	v_mov_b32_e32 v38, v36
	v_pk_add_f32 v[36:37], v[52:53], v[38:39]
	v_mov_b32_e32 v55, v40
	v_sub_f32_e32 v40, v56, v195
	s_nop 1
	v_exp_f32_e32 v40, v40
	v_exp_f32_e32 v50, v41
	v_mov_b32_e32 v41, v40
	v_mov_b32_e32 v54, v50
	v_sub_f32_e32 v40, v57, v195
	v_cvt_pk_bf16_f32 v52, v55, v54
	s_nop 0
	v_exp_f32_e32 v40, v40
	s_nop 0
	v_exp_f32_e32 v42, v42
	v_mov_b32_e32 v40, v40
	v_pk_add_f32 v[50:51], v[54:55], v[40:41]
	v_mov_b32_e32 v65, v42
	v_sub_f32_e32 v42, v58, v195
	s_nop 1
	v_exp_f32_e32 v42, v42
	v_exp_f32_e32 v56, v43
	v_mov_b32_e32 v43, v42
	v_mov_b32_e32 v64, v56
	v_sub_f32_e32 v42, v59, v195
	v_cvt_pk_bf16_f32 v53, v65, v64
	s_nop 0
	v_exp_f32_e32 v42, v42
	s_nop 0
	v_exp_f32_e32 v44, v44
	v_mov_b32_e32 v42, v42
	v_pk_add_f32 v[56:57], v[64:65], v[42:43]
	v_mov_b32_e32 v67, v44
	v_sub_f32_e32 v44, v60, v195
	s_nop 1
	v_exp_f32_e32 v44, v44
	v_exp_f32_e32 v58, v45
	v_mov_b32_e32 v45, v44
	v_mov_b32_e32 v66, v58
	v_sub_f32_e32 v44, v61, v195
	v_cvt_pk_bf16_f32 v54, v67, v66
	s_nop 1
	v_exp_f32_e32 v44, v44
	s_nop 0
	v_exp_f32_e32 v46, v46
	v_mov_b32_e32 v44, v44
	v_pk_add_f32 v[58:59], v[66:67], v[44:45]
	v_mov_b32_e32 v61, v46
	v_sub_f32_e32 v46, v62, v195
	s_nop 1
	v_exp_f32_e32 v62, v46
	v_sub_f32_e32 v46, v47, v195
	s_nop 1
	v_exp_f32_e32 v46, v46
	s_nop 0
	v_mov_b32_e32 v60, v71
	v_exp_f32_e32 v71, v60
	v_mov_b32_e32 v60, v46
	v_sub_f32_e32 v47, v63, v195
	v_and_b32_e32 v63, 0xffff, v168
	v_mov_b32_e32 v46, v71
	v_lshl_or_b32 v63, v172, 16, v63
	v_add_u32_e32 v71, v181, v224
	ds_write2_b32 v71, v63, v72 offset1:36
	v_and_b32_e32 v63, 0xffff, v169
	v_lshrrev_b32_e32 v72, 16, v169
	v_lshl_or_b32 v63, v173, 16, v63
	v_and_or_b32 v72, v173, s31, v72
	ds_write2_b32 v71, v63, v72 offset0:72 offset1:108
	v_and_b32_e32 v63, 0xffff, v170
	v_lshrrev_b32_e32 v72, 16, v170
	v_lshl_or_b32 v63, v174, 16, v63
	v_and_or_b32 v72, v174, s31, v72
	ds_write2_b32 v71, v63, v72 offset0:144 offset1:180
	v_and_b32_e32 v63, 0xffff, v171
	v_lshrrev_b32_e32 v72, 16, v171
	v_lshl_or_b32 v63, v175, 16, v63
	v_and_or_b32 v72, v175, s31, v72
	ds_write2_b32 v71, v63, v72 offset0:216 offset1:252
	v_and_b32_e32 v63, 0xffff, v160
	v_lshrrev_b32_e32 v72, 16, v160
	s_waitcnt vmcnt(2)
	v_lshl_or_b32 v63, v164, 16, v63
	v_add_u32_e32 v71, v181, v225
	v_and_or_b32 v72, v164, s31, v72
	ds_write2_b32 v71, v63, v72 offset1:36
	v_and_b32_e32 v63, 0xffff, v161
	v_lshrrev_b32_e32 v72, 16, v161
	v_lshl_or_b32 v63, v165, 16, v63
	v_and_or_b32 v72, v165, s31, v72
	ds_write2_b32 v71, v63, v72 offset0:72 offset1:108
	v_and_b32_e32 v63, 0xffff, v162
	v_lshrrev_b32_e32 v72, 16, v162
	v_lshl_or_b32 v63, v166, 16, v63
	v_and_or_b32 v72, v166, s31, v72
	ds_write2_b32 v71, v63, v72 offset0:144 offset1:180
	v_and_b32_e32 v63, 0xffff, v163
	v_lshrrev_b32_e32 v72, 16, v163
	v_lshl_or_b32 v63, v167, 16, v63
	v_and_or_b32 v72, v167, s31, v72
	ds_write2_b32 v71, v63, v72 offset0:216 offset1:252
	s_waitcnt vmcnt(3)
	v_and_b32_e32 v63, 0xffff, v152
	v_lshrrev_b32_e32 v72, 16, v152
	s_waitcnt vmcnt(1)
	v_lshl_or_b32 v63, v156, 16, v63
	v_and_or_b32 v72, v156, s31, v72
	v_add_u32_e32 v73, 0x800, v71
	ds_write2_b32 v73, v63, v72 offset0:64 offset1:100
	v_and_b32_e32 v63, 0xffff, v153
	v_lshrrev_b32_e32 v72, 16, v153
	v_lshl_or_b32 v63, v157, 16, v63
	v_and_or_b32 v72, v157, s31, v72
	ds_write2_b32 v73, v63, v72 offset0:136 offset1:172
	v_and_b32_e32 v63, 0xffff, v154
	v_lshrrev_b32_e32 v72, 16, v154
	v_lshl_or_b32 v63, v158, 16, v63
	v_and_or_b32 v72, v158, s31, v72
	ds_write2_b32 v73, v63, v72 offset0:208 offset1:244
	v_and_b32_e32 v63, 0xffff, v155
	v_lshrrev_b32_e32 v72, 16, v155
	v_lshl_or_b32 v63, v159, 16, v63
	v_and_or_b32 v72, v159, s31, v72
	v_add_u32_e32 v73, 0xc00, v71
	ds_write2_b32 v73, v63, v72 offset0:24 offset1:60
	v_and_b32_e32 v63, 0xffff, v144
	v_lshrrev_b32_e32 v72, 16, v144
	s_waitcnt vmcnt(0)
	v_lshl_or_b32 v63, v148, 16, v63
	v_and_or_b32 v72, v148, s31, v72
	v_add_u32_e32 v73, 0x1000, v71
	ds_write2_b32 v73, v63, v72 offset0:128 offset1:164
	v_and_b32_e32 v63, 0xffff, v145
	v_lshrrev_b32_e32 v72, 16, v145
	v_lshl_or_b32 v63, v149, 16, v63
	v_and_or_b32 v72, v149, s31, v72
	ds_write2_b32 v73, v63, v72 offset0:200 offset1:236
	v_and_b32_e32 v63, 0xffff, v146
	v_lshrrev_b32_e32 v72, 16, v146
	v_lshl_or_b32 v63, v150, 16, v63
	v_and_or_b32 v72, v150, s31, v72
	v_add_u32_e32 v71, 0x1400, v71
	ds_write2_b32 v71, v63, v72 offset0:16 offset1:52
	v_and_b32_e32 v63, 0xffff, v147
	v_lshrrev_b32_e32 v72, 16, v147
	v_lshl_or_b32 v63, v151, 16, v63
	v_and_or_b32 v72, v151, s31, v72
	ds_write2_b32 v71, v63, v72 offset0:88 offset1:124
	s_waitcnt lgkmcnt(0)
	ds_read_b128 v[72:75], v93
	ds_read_b128 v[80:83], v93 offset:32
	ds_read_b128 v[84:87], v93 offset:4608
	v_pk_mul_f32 v[30:31], v[30:31], v[46:47] op_sel_hi:[1,0]
	v_pk_mul_f32 v[28:29], v[28:29], v[46:47] op_sel_hi:[1,0]
	v_pk_mul_f32 v[26:27], v[26:27], v[46:47] op_sel_hi:[1,0]
	v_pk_mul_f32 v[24:25], v[24:25], v[46:47] op_sel_hi:[1,0]
	v_pk_mul_f32 v[22:23], v[22:23], v[46:47] op_sel_hi:[1,0]
	v_pk_mul_f32 v[20:21], v[20:21], v[46:47] op_sel_hi:[1,0]
	v_pk_mul_f32 v[18:19], v[18:19], v[46:47] op_sel_hi:[1,0]
	v_pk_mul_f32 v[16:17], v[16:17], v[46:47] op_sel_hi:[1,0]
	v_pk_mul_f32 v[14:15], v[14:15], v[46:47] op_sel_hi:[1,0]
	v_pk_mul_f32 v[12:13], v[12:13], v[46:47] op_sel_hi:[1,0]
	s_waitcnt lgkmcnt(2)
	v_mfma_f32_32x32x16_bf16 v[16:31], v[72:75], v[76:79], v[16:31]
	v_mul_f32_e64 v10, v10, v46
	v_mul_f32_e64 v11, v11, v46
	v_mul_f32_e64 v8, v8, v46
	v_mul_f32_e64 v9, v9, v46
	v_mul_f32_e64 v6, v6, v46
	v_mul_f32_e64 v7, v7, v46
	v_pk_mul_f32 v[4:5], v[4:5], v[46:47] op_sel_hi:[1,0]
	v_pk_mul_f32 v[2:3], v[2:3], v[46:47] op_sel_hi:[1,0]
	v_pk_mul_f32 v[0:1], v[0:1], v[46:47] op_sel_hi:[1,0]
	ds_read_b128 v[72:75], v93 offset:4640
	s_nop 0
	s_waitcnt lgkmcnt(1)
	v_mfma_f32_32x32x16_bf16 v[0:15], v[84:87], v[76:79], v[0:15]
	v_cvt_pk_bf16_f32 v55, v61, v60
	v_exp_f32_e32 v47, v47
	v_mov_b32_e32 v49, v62
	v_mov_b32_e32 v48, v47
	v_pk_add_f32 v[76:77], v[60:61], v[48:49]
	ds_read_b128 v[60:63], v93 offset:64
	v_mfma_f32_32x32x16_bf16 v[16:31], v[80:83], v[52:55], v[16:31]
	v_add_f32_e32 v47, v68, v70
	s_waitcnt lgkmcnt(1)
	v_mfma_f32_32x32x16_bf16 v[0:15], v[72:75], v[52:55], v[0:15]
	v_cvt_pk_bf16_f32 v54, v35, v34
	v_add_f32_e32 v34, v47, v69
	v_add_f32_e32 v34, v90, v34
	v_cvt_pk_bf16_f32 v52, v70, v88
	ds_read_b128 v[64:67], v93 offset:4672
	ds_read_b128 v[70:73], v93 offset:96
	v_add_f32_e32 v34, v92, v34
	v_add_f32_e32 v33, v33, v34
	v_add_f32_e32 v32, v32, v33
	v_add_f32_e32 v37, v37, v32
	ds_read_b128 v[32:35], v93 offset:4704
	v_cvt_pk_bf16_f32 v53, v89, v91
	v_cvt_pk_bf16_f32 v55, v39, v38
	v_add_f32_e32 v36, v36, v37
	s_waitcnt lgkmcnt(3)
	v_mfma_f32_32x32x16_bf16 v[16:31], v[60:63], v[52:55], v[16:31]
	v_add_f32_e32 v36, v51, v36
	v_add_f32_e32 v47, v50, v36
	v_cvt_pk_bf16_f32 v36, v41, v40
	v_cvt_pk_bf16_f32 v37, v43, v42
	v_cvt_pk_bf16_f32 v38, v45, v44
	v_cvt_pk_bf16_f32 v39, v49, v48
	s_waitcnt lgkmcnt(0)
	s_waitcnt lgkmcnt(2)
	v_mfma_f32_32x32x16_bf16 v[0:15], v[64:67], v[52:55], v[0:15]
	s_waitcnt lgkmcnt(0)
	v_mfma_f32_32x32x16_bf16 v[0:15], v[32:35], v[36:39], v[0:15]
	v_add_f32_e32 v32, v57, v47
	v_add_f32_e32 v32, v56, v32
	v_add_f32_e32 v32, v59, v32
	v_add_f32_e32 v32, v58, v32
	v_add_f32_e32 v32, v77, v32
	v_add_f32_e32 v144, v76, v32
	v_fmac_f32_e32 v144, v233, v46
	v_mfma_f32_32x32x16_bf16 v[16:31], v[70:73], v[36:39], v[16:31]
	s_cbranch_scc1 .LBB0_812
	v_mov_b64_e32 v[178:179], v[114:115]
	v_mov_b64_e32 v[32:33], v[116:117]
	v_mov_b64_e32 v[36:37], v[124:125]
	v_mov_b64_e32 v[40:41], v[120:121]
	v_mov_b64_e32 v[44:45], v[128:129]
	v_mov_b64_e32 v[48:49], v[132:133]
	v_mov_b64_e32 v[56:57], v[140:141]
	v_mov_b64_e32 v[52:53], v[136:137]
	v_mov_b64_e32 v[176:177], v[112:113]
	v_mov_b64_e32 v[34:35], v[118:119]
	v_mov_b64_e32 v[38:39], v[126:127]
	v_mov_b64_e32 v[42:43], v[122:123]
	v_mov_b64_e32 v[46:47], v[130:131]
	v_mov_b64_e32 v[50:51], v[134:135]
	v_mov_b64_e32 v[58:59], v[142:143]
	v_mov_b64_e32 v[54:55], v[138:139]
	v_mov_b32_e32 v234, v195
	v_mov_b32_e32 v233, v144
	s_branch .LBB0_804
